# XCD-local row panels in all M=8192 GEMM phases + panel-local softmax/gate-GEMM rows; barriers after OUT/softmax/UP are XCD-local, chain barriers skip L2 write-back; conv loops counted vmcnt
# speedup vs baseline: 1.0022x; 1.0022x over previous
; #define LAS __attribute__((address_space(3)))
; #define LAS __attribute__((address_space(3)))
; __device__ __forceinline__ unsigned xb_add(unsigned* p, unsigned v) { return __hip_atomic_fetch_add(p, v, __ATOMIC_RELAXED, __HIP_MEMORY_SCOPE_AGENT); }
; __device__ __forceinline__ unsigned xb_xcc_id() { return (unsigned)__builtin_amdgcn_s_getreg((3 << 11) | 20) & 0xFu; }
; __device__ __forceinline__ XcdBarrier xcd_barrier_post(unsigned* bar, volatile LAS unsigned* st) {
;     XcdBarrier b; b.bar = bar; b.x = xb_xcc_id(); b.st = st;
;     if (threadIdx.x == 0) (void)xb_add(&bar[XB_XCNT(b.x)], 1u);
;     return b;
; }
; __global__ void __launch_bounds__(NTHREADS, 2) fwd(Args args) {
;     ...
;     XcdBarrier bar; bar.bar = (unsigned*)(ws_top + WS_CTL) + CW_BAR; bar.x = 0; bar.st = nullptr;
;     const bool one_launch = (hi - lo) > 1;
;     if (one_launch) bar = xcd_barrier_post((unsigned*)(ws_top + WS_CTL) + CW_BAR, (volatile LAS unsigned*)(F.lds + MISC_OFF) + 8);
.LBB0_6:
	s_or_b64 exec, exec, s[12:13]
	s_add_u32 s0, s60, 0x4000
	s_addc_u32 s1, s61, 0
	s_sub_i32 s3, s63, s62
	s_cmp_gt_i32 s3, 1
	s_cselect_b64 s[4:5], -1, 0
	v_writelane_b32 v252, s4, 5
	v_readfirstlane_b32 s7, v0
	s_mov_b32 s97, 0
	s_mov_b32 s6, 0
	v_writelane_b32 v252, s5, 6
	s_cmp_lt_i32 s3, 2
	v_cmp_eq_u32_e32 vcc, 0, v0
	s_mov_b32 s3, 0
	s_waitcnt lgkmcnt(0)
	s_barrier
	v_writelane_b32 v252, s3, 7
	s_cbranch_scc1 .LBB0_11
	s_getreg_b32 s3, hwreg(HW_REG_XCC_ID, 0, 4)
	s_and_b32 s6, s3, 15
	s_and_saveexec_b64 s[10:11], vcc
	s_cbranch_execz .LBB0_10
	s_mov_b64 s[4:5], exec
	v_mbcnt_lo_u32_b32 v1, s4, 0
	v_mbcnt_hi_u32_b32 v1, s5, v1
	v_cmp_eq_u32_e32 vcc, 0, v1
	s_and_b64 s[8:9], exec, vcc
	s_mov_b64 exec, s[8:9]
	s_cbranch_execz .LBB0_10
	s_lshl_b32 s8, s6, 8
	s_bcnt1_i32_b64 s4, s[4:5]
	v_mov_b32_e32 v1, s8
	v_mov_b32_e32 v2, s4
	global_atomic_add v2, v1, v2, s[0:1] offset:1024 sc0
	s_waitcnt vmcnt(0)
	v_and_b32_e32 v1, 3, v2
	v_lshl_add_u32 v1, s6, 2, v1
	v_bfe_u32 v3, v2, 2, 1
	v_lshrrev_b32_e32 v4, 3, v2
	v_and_b32_e32 v5, 7, v1
	v_lshl_add_u32 v5, v4, 3, v5
	v_lshrrev_b32_e32 v6, 3, v1
	v_lshl_add_u32 v6, v6, 1, v3
	v_lshl_add_u32 v5, v5, 3, v6
	v_lshl_add_u32 v6, v3, 2, v4
	v_lshl_add_u32 v7, v1, 3, v6
	v_lshlrev_b32_e32 v8, 5, v7
	v_mov_b32_e32 v9, 0x23200
	ds_write_b32 v9, v5
	ds_write_b32 v9, v7 offset:4
	ds_write_b32 v9, v8 offset:8
	s_waitcnt lgkmcnt(0)

; #define CONV_LOAD(d_, wv_, g0_, g1_) do { _Pragma("unroll") for (int i_ = 0; i_ < 8; ++i_) wv_[i_] = *(const GAS f32x4*)((d_).src + (size_t)(8 * i_) * (d_).N); \
;         g0_ = (f32x4){1.f, 1.f, 1.f, 1.f}; g1_ = g0_; if ((d_).gk) { g0_ = *(const GAS f32x4*)(d_).gk; g1_ = *(const GAS f32x4*)((d_).gk + 4); } } while (0)
; __device__ __forceinline__ void conv_weights_phase(const Frame& F, const float* const CAS* inp, unsigned char* ws, const SegC* segs, const int* starts, int nseg, int per_layer, int f_begin, int f_end, LAS float* scr, int gw, int NGW) {
;     ...
;                 int f = f_begin + gw;
;                 if (f < nflat) { CONV_DESC(f, dA); CONV_LOAD(dA, wA, gA0, gA1); }
;                 while (f < nflat) {
;                     const int f1 = f + NGW;
;                     if (f1 < nflat) { CONV_DESC(f1, dB); CONV_LOAD(dB, wB, gB0, gB1); }
;                     CONV_STORE(dA, wA, gA0, gA1);
;                     if (f1 >= nflat) break;
;                     const int f2 = f1 + NGW;
;                     if (f2 < nflat) { CONV_DESC(f2, dA); CONV_LOAD(dA, wA, gA0, gA1); }
;                     CONV_STORE(dB, wB, gB0, gB1);
;                     f = f2;
;                 }
.Lcv1_q2:
	s_waitcnt vmcnt(0)
	s_branch .LBB0_69
.LBB0_82:
	s_branch .LBB0_71

; #define CONV_LOAD(d_, wv_, g0_, g1_) do { _Pragma("unroll") for (int i_ = 0; i_ < 8; ++i_) wv_[i_] = *(const GAS f32x4*)((d_).src + (size_t)(8 * i_) * (d_).N); \
;         g0_ = (f32x4){1.f, 1.f, 1.f, 1.f}; g1_ = g0_; if ((d_).gk) { g0_ = *(const GAS f32x4*)(d_).gk; g1_ = *(const GAS f32x4*)((d_).gk + 4); } } while (0)
; __device__ __forceinline__ void conv_weights_phase(const Frame& F, const float* const CAS* inp, unsigned char* ws, const SegC* segs, const int* starts, int nseg, int per_layer, int f_begin, int f_end, LAS float* scr, int gw, int NGW) {
;     ...
;                 int f = f_begin + gw;
;                 if (f < nflat) { CONV_DESC(f, dA); CONV_LOAD(dA, wA, gA0, gA1); }
;                 while (f < nflat) {
;                     const int f1 = f + NGW;
;                     if (f1 < nflat) { CONV_DESC(f1, dB); CONV_LOAD(dB, wB, gB0, gB1); }
;                     CONV_STORE(dA, wA, gA0, gA1);
;                     if (f1 >= nflat) break;
;                     const int f2 = f1 + NGW;
;                     if (f2 < nflat) { CONV_DESC(f2, dA); CONV_LOAD(dA, wA, gA0, gA1); }
;                     CONV_STORE(dB, wB, gB0, gB1);
;                     f = f2;
;                 }
.Lcv4_q2:
	s_waitcnt vmcnt(0)
	s_branch .LBB0_222
.LBB0_235:
	s_branch .LBB0_224

; #define CONV_LOAD(d_, wv_, g0_, g1_) do { _Pragma("unroll") for (int i_ = 0; i_ < 8; ++i_) wv_[i_] = *(const GAS f32x4*)((d_).src + (size_t)(8 * i_) * (d_).N); \
;         g0_ = (f32x4){1.f, 1.f, 1.f, 1.f}; g1_ = g0_; if ((d_).gk) { g0_ = *(const GAS f32x4*)(d_).gk; g1_ = *(const GAS f32x4*)((d_).gk + 4); } } while (0)
; __device__ __forceinline__ void conv_weights_phase(const Frame& F, const float* const CAS* inp, unsigned char* ws, const SegC* segs, const int* starts, int nseg, int per_layer, int f_begin, int f_end, LAS float* scr, int gw, int NGW) {
;     ...
;                 int f = f_begin + gw;
;                 if (f < nflat) { CONV_DESC(f, dA); CONV_LOAD(dA, wA, gA0, gA1); }
;                 while (f < nflat) {
;                     const int f1 = f + NGW;
;                     if (f1 < nflat) { CONV_DESC(f1, dB); CONV_LOAD(dB, wB, gB0, gB1); }
;                     CONV_STORE(dA, wA, gA0, gA1);
;                     if (f1 >= nflat) break;
;                     const int f2 = f1 + NGW;
;                     if (f2 < nflat) { CONV_DESC(f2, dA); CONV_LOAD(dA, wA, gA0, gA1); }
;                     CONV_STORE(dB, wB, gB0, gB1);
;                     f = f2;
;                 }
.Lcv5_q2:
	s_waitcnt vmcnt(0)
	s_branch .LBB0_376
.LBB0_389:
	s_branch .LBB0_378

;     __host__ __device__ bool next(int i, Unit& u) const { if (!StaticOrder::next(i, u)) return false; u.nt = nt8 + ntb; return true; }
; #define LAS __attribute__((address_space(3)))
; #define LAS __attribute__((address_space(3)))
; #define AMP_T0() const unsigned long long at0_ = (PROBE_AMP != 0) ? __builtin_amdgcn_s_memrealtime() : 0ull
;     __host__ __device__ bool next(int i, Unit& u) const {
;         if (i >= nr) return false;
;         const long L = (long)(i + r0) * G + c; if (L >= nwg) return false;
;         int wgid = (int)L; { const int q = nwg / NXCD, r = nwg % NXCD, xcd = wgid % NXCD, off = wgid / NXCD; wgid = (xcd < r ? xcd * (q + 1) : r * (q + 1) + (xcd - r) * q) + off; }
;         const int nig = WGM * nN, gid = wgid / nig, fm = gid * WGM, gsz = (nM - fm) < WGM ? (nM - fm) : WGM;
;         u.pm = fm + ((wgid % nig) % gsz); u.pn = (wgid % nig) / gsz; u.om = u.pm; u.on = u.pn; u.kind = 0; u.aoff = 0; u.boff = 0; return true;
; __global__ void __launch_bounds__(NTHREADS, 2) fwd(Args args) {
;     ...
;         if (IN(pb + PH_IN)) { PHASE_BEGIN(); AMP_T0();
;             pg8::Gemm g{XN, (const bf16*)(wl + WL_IN), M, NPB, D, 0, 0}; pg8::StaticOrder S; S.init(M, NPB, F.G, F.bx);
;             pg8::EpiBf16<0> E{(bf16*)(ws + WS_PB), NPB, nullptr, 0, RS, M, 1.f / D, EPS, (LAS float*)(F.lds + RING_BYTES), 0, (LAS int*)(F.lds + MISC_OFF) + 16, (l * 4 + 1) * 64};
;             pg8::gemm_phase<pg8::EpiBf16<0>, pg8::StaticOrder, true, true>(F.lds + RING_OFF, g, S, E, F.tid);
.LBB0_498:
	v_readlane_b32 s0, v251, 40
	s_add_i32 s12, s0, 2
	s_cmp_le_i32 s62, s12
	s_cselect_b64 s[10:11], -1, 0
	s_cmp_lt_i32 s12, s63
	s_cselect_b64 s[12:13], -1, 0
	s_and_b64 s[10:11], s[10:11], s[12:13]
	s_mov_b32 s1, 0x800000
	s_movk_i32 s92, 0x4000
	s_andn2_b64 vcc, exec, s[10:11]
	s_cbranch_vccnz .LBB0_556
	v_readlane_b32 s10, v252, 1
	v_readlane_b32 s11, v252, 2
	s_mov_b32 s12, -1
	v_readlane_b32 s18, v251, 41
	v_readlane_b32 s28, v252, 0
	v_mov_b32_e32 v0, 0x23200
	ds_read_b32 v0, v0
	s_waitcnt lgkmcnt(0)
	v_readfirstlane_b32 s30, v0
	s_nop 1
	v_readlane_b32 s0, v252, 8
	s_waitcnt vmcnt(0)
	v_mbcnt_lo_u32_b32 v0, s12, 0
	v_mbcnt_hi_u32_b32 v0, s12, v0
	v_add_u32_e32 v65, s0, v0
	s_cmpk_lt_i32 s30, 0x200
	v_mov_b32_e32 v14, v65
	v_readfirstlane_b32 s27, v65
	s_cselect_b64 s[12:13], -1, 0
	s_cmpk_gt_i32 s30, 0x1ff
	v_readfirstlane_b32 s20, v14
	s_cbranch_scc1 .LBB0_505
	s_ashr_i32 s14, s30, 31
	s_lshr_b32 s14, s14, 29
	s_add_i32 s16, s30, s14
	s_and_b32 s14, s16, -8
	s_sub_i32 s17, s30, s14
	s_cmp_gt_i32 s17, -1
	s_mov_b64 s[14:15], -1
	s_cbranch_scc0 .LBB0_502
	s_lshl_b32 s19, s17, 6
	s_mov_b64 s[14:15], 0

; #define LAS __attribute__((address_space(3)))
; #define LAS __attribute__((address_space(3)))
; __device__ __forceinline__ void zgemm(const Frame& F, const bf16* XN, const bf16* WZ, const float* RS, float* Z) {
;     const int lane = F.lane, g = lane >> 4, c = lane & 15, w = F.wave, kq = w & 3;
;     LAS f32x4* red = (LAS f32x4*)F.lds;
;     for (int rb = F.bx; rb < M / 32; rb += F.G) {
;         const int rt = rb * 2 + (w >> 2);
;         const bf16* ap = XN + (size_t)(rt * 16 + c) * D + kq * 512 + g * 8;
;         const bf16* b0 = WZ + (size_t)c * D + kq * 512 + g * 8; const bf16* b1p = WZ + (size_t)(16 + c) * D + kq * 512 + g * 8;
.LBB0_549:
	v_mov_b32_e32 v0, 0x23204
	ds_read_b32 v0, v0
	s_waitcnt lgkmcnt(0)
	v_readfirstlane_b32 s30, v0
	s_nop 1
	v_readlane_b32 s52, v251, 21
	s_cmpk_gt_i32 s30, 0xff
	v_readlane_b32 s53, v251, 22
	s_cbranch_scc1 .LBB0_556
	s_ashr_i32 s12, s27, 6
	s_lshl_b32 s13, s12, 2
	s_lshl_b32 s20, s12, 11
	s_and_b32 s17, s12, 3
	s_and_b32 s16, s13, -16
	s_add_i32 s12, s20, 0
	v_lshlrev_b32_e32 v0, 4, v65
	v_and_b32_e32 v0, 0x3f0, v0
	s_cmp_eq_u32 s17, 0
	v_add_u32_e32 v86, s12, v0
	s_cselect_b64 s[12:13], -1, 0
	s_lshl_b32 s17, s17, 10
	v_and_b32_e32 v4, 15, v65
	v_add_u32_e32 v5, 0, v0
	v_lshrrev_b32_e32 v0, 2, v65
	s_add_u32 s18, s14, s31
	v_and_b32_e32 v87, 12, v0
	v_lshlrev_b32_e32 v0, 2, v4
	v_mov_b32_e32 v1, v64
	s_addc_u32 s19, s15, s34
	v_lshl_add_u64 v[0:1], s[14:15], 0, v[0:1]
	s_mov_b64 s[0:1], 0x27500000
	s_add_u32 s14, s14, s17
	v_lshlrev_b32_e32 v2, 12, v4
	v_lshl_add_u64 v[8:9], v[0:1], 0, s[0:1]
	v_and_b32_e32 v0, 48, v65
	v_mov_b32_e32 v1, v64
	s_addc_u32 s15, s15, 0
	v_or3_b32 v2, v2, s17, v0
	v_lshl_add_u64 v[0:1], s[14:15], 0, v[0:1]
	s_mov_b64 s[14:15], 0x1e500100
	v_lshl_add_u64 v[12:13], v[0:1], 0, s[14:15]
	s_lshl_b32 s14, s30, 5
	v_mov_b32_e32 v3, v64
	s_add_i32 s14, s14, s16
	v_lshl_add_u64 v[10:11], s[18:19], 0, v[2:3]
	v_or_b32_e32 v14, s14, v4
	s_lshl_b32 s17, s28, 5
	v_add_u32_e32 v65, s20, v5
	s_branch .LBB0_552

;     __host__ __device__ bool next(int i, Unit& u) const { if (!StaticOrder::next(i, u)) return false; u.nt = nt8 + ntb; return true; }
; #define AMP_T0() const unsigned long long at0_ = (PROBE_AMP != 0) ? __builtin_amdgcn_s_memrealtime() : 0ull
; #define AMP_END(bit) do { if (PROBE_AMP & (1u << (bit))) { __syncthreads(); const unsigned long long at1_ = __builtin_amdgcn_s_memrealtime(), tgt_ = at1_ + AMP_K * (at1_ - at0_); \
;         while (__builtin_amdgcn_s_memrealtime() < tgt_) __builtin_amdgcn_s_sleep(16); } } while (0)
;     __host__ __device__ bool next(int i, Unit& u) const {
;         if (i >= nr) return false;
;         const long L = (long)(i + r0) * G + c; if (L >= nwg) return false;
;         int wgid = (int)L; { const int q = nwg / NXCD, r = nwg % NXCD, xcd = wgid % NXCD, off = wgid / NXCD; wgid = (xcd < r ? xcd * (q + 1) : r * (q + 1) + (xcd - r) * q) + off; }
;         const int nig = WGM * nN, gid = wgid / nig, fm = gid * WGM, gsz = (nM - fm) < WGM ? (nM - fm) : WGM;
;         u.pm = fm + ((wgid % nig) % gsz); u.pn = (wgid % nig) / gsz; u.om = u.pm; u.on = u.pn; u.kind = 0; u.aoff = 0; u.boff = 0; return true;
; __global__ void __launch_bounds__(NTHREADS, 2) fwd(Args args) {
;     ...
;         if (IN(pb + PH_OUT)) { PHASE_BEGIN(); AMP_T0();
;             pg8::Gemm g{(const bf16*)(ws + WS_MIX), (const bf16*)(wl + WL_OUT), M, D, D, 0, 0}; pg8::StaticOrder S; S.init(M, D, F.G, F.bx);
;             pg8::EpiResid E{XN, ka_->in[25] + (size_t)l * D, RS, M, nullptr, (float*)(ws + WS_SLOT) + (size_t)(l * 3 + 0) * 32 * 8 * 256, (unsigned*)(ws + WS_CTL) + CW_RCNT + (l * 3 + 0) * 32 * 64, 1.f / D, EPS};
;             pg8::gemm_phase<pg8::EpiResid, pg8::StaticOrder, false, true>(F.lds + RING_OFF, g, S, E, F.tid); AMP_END(9);
.LBB0_897:
	s_cmp_le_i32 s62, s27
	s_cselect_b64 s[12:13], -1, 0
	s_and_b64 s[10:11], s[12:13], s[10:11]
	s_andn2_b64 vcc, exec, s[10:11]
	s_cbranch_vccnz .LBB0_972
	v_readlane_b32 s12, v252, 1
	v_readlane_b32 s13, v252, 2
	v_mov_b32_e32 v0, 0x23200
	ds_read_b32 v0, v0
	s_waitcnt lgkmcnt(0)
	v_readfirstlane_b32 s28, v0
	s_nop 1
	s_mov_b32 s10, -1
	s_mov_b32 s16, s3
	v_readlane_b32 s30, v252, 0
	v_readlane_b32 s0, v252, 8
	s_waitcnt vmcnt(0)
	v_mbcnt_lo_u32_b32 v0, s10, 0
	v_mbcnt_hi_u32_b32 v0, s10, v0
	v_add_u32_e32 v168, s0, v0
	s_cmpk_gt_i32 s28, 0xff
	s_nop 0
	v_readfirstlane_b32 s27, v168
	s_cbranch_scc1 .LBB0_972
	s_ashr_i32 s31, s28, 31
	s_lshr_b32 s10, s31, 29
	s_add_i32 s19, s28, s10
	s_and_b32 s10, s19, -8
	s_sub_i32 s17, s28, s10
	s_cmp_gt_i32 s17, -1
	s_mov_b64 s[14:15], -1
	s_cbranch_scc0 .LBB0_901
	s_lshl_b32 s18, s17, 5
	s_mov_b64 s[14:15], 0

; __device__ __forceinline__ unsigned xb_ld(unsigned* p)              { return __hip_atomic_load(p, __ATOMIC_RELAXED, __HIP_MEMORY_SCOPE_AGENT); }
; __device__ __forceinline__ unsigned xb_add(unsigned* p, unsigned v) { return __hip_atomic_fetch_add(p, v, __ATOMIC_RELAXED, __HIP_MEMORY_SCOPE_AGENT); }
; #define XB_SPIN(cond, bar) do { unsigned _sp = 0; while (cond) { __builtin_amdgcn_s_sleep(1); \
;     if ((++_sp & 255u) == 0u) { if (xb_ld(&(bar)[XB_TMO])) break; if (_sp > XB_SPIN_CAP) { atomicAdd(&(bar)[XB_TMO], 1u); break; } } } } while (0)
; __device__ __forceinline__ void xcd_barrier(const XcdBarrier& b) {
;     ...
;         const unsigned old = xb_add(&bar[XB_XSUB(b.x)], 1u);
;         const unsigned gen = old / nloc;
;         if (old + 1u == (gen + 1u) * nloc) {
;             __builtin_amdgcn_fence(__ATOMIC_RELEASE, "agent");
;             asm volatile("s_waitcnt vmcnt(0)" ::: "memory");
;             const unsigned og = xb_add(&bar[XB_TOP], 1u);
;             const unsigned tg = og / nx;
;             if (og + 1u == (tg + 1u) * nx) xb_add(&bar[XB_TOPGEN], 1u);
;             else XB_SPIN(xb_ld(&bar[XB_TOPGEN]) == tg, bar);
;             __builtin_amdgcn_fence(__ATOMIC_ACQUIRE, "agent");
;             xb_add(&bar[XB_XGEN(b.x)], 1u);
.LBB0_1003:
	s_andn2_saveexec_b64 s[14:15], s[14:15]
	s_cbranch_execz .LBB0_1021
	s_mov_b64 s[14:15], exec
	s_branch .Lxl_0
	s_waitcnt lgkmcnt(0)
	s_waitcnt vmcnt(0)
	v_mbcnt_lo_u32_b32 v1, s14, 0
	v_mbcnt_hi_u32_b32 v1, s15, v1
	v_cmp_eq_u32_e32 vcc, 0, v1
	s_and_saveexec_b64 s[16:17], vcc
	s_cbranch_execz .LBB0_1006
	s_bcnt1_i32_b64 s14, s[14:15]
	v_readlane_b32 s0, v252, 57
	v_mov_b32_e32 v2, s14
	v_readlane_b32 s1, v252, 58
	s_nop 4
	global_atomic_add v2, v64, v2, s[0:1] sc0

; __device__ __forceinline__ unsigned xb_add(unsigned* p, unsigned v) { return __hip_atomic_fetch_add(p, v, __ATOMIC_RELAXED, __HIP_MEMORY_SCOPE_AGENT); }
; __device__ __forceinline__ void xcd_barrier(const XcdBarrier& b) {
;     ...
;             __builtin_amdgcn_fence(__ATOMIC_ACQUIRE, "agent");
;             xb_add(&bar[XB_XGEN(b.x)], 1u);
;             asm volatile("s_waitcnt vmcnt(0)" ::: "memory");
.Lxl_0:
	v_readlane_b32 s0, v252, 55
	v_readlane_b32 s1, v252, 56
	s_waitcnt vmcnt(0)
	buffer_inv sc1
	s_nop 2
	global_atomic_add v64, v219, s[0:1]
	s_waitcnt vmcnt(0)

;     __host__ __device__ bool next(int i, Unit& u) const { if (!StaticOrder::next(i, u)) return false; u.nt = nt8 + ntb; return true; }
; #define LAS __attribute__((address_space(3)))
; #define LAS __attribute__((address_space(3)))
; #define AMP_T0() const unsigned long long at0_ = (PROBE_AMP != 0) ? __builtin_amdgcn_s_memrealtime() : 0ull
; #define AMP_END(bit) do { if (PROBE_AMP & (1u << (bit))) { __syncthreads(); const unsigned long long at1_ = __builtin_amdgcn_s_memrealtime(), tgt_ = at1_ + AMP_K * (at1_ - at0_); \
;         while (__builtin_amdgcn_s_memrealtime() < tgt_) __builtin_amdgcn_s_sleep(16); } } while (0)
;     __host__ __device__ bool next(int i, Unit& u) const {
;         if (!StaticOrder::next(i, u)) return false;
;         const int b = u.pm >> 3, slot = u.pn, pn = SPLITK == 2 ? slot >> 1 : slot, kh = SPLITK == 2 ? (slot & 1) : 0;
;         u.pn = bp0 + b * per_b + pn; u.on = pn; u.om = kh * nM + u.pm; u.aoff = kh * khalf_bytes; u.boff = kh * khalf_bytes;
;         return true;
;     }
; __global__ void __launch_bounds__(NTHREADS, 2) fwd(Args args) {
;     ...
;         if (IN(pb + PH_Q)) { PHASE_BEGIN(); AMP_T0();
;             pg8::Gemm g{XN, (const bf16*)(ws + WS_MQK), M, 2048, 1024, D, D}; pg8::BatchBOrder<2> S; S.init(M, 2048, F.G, F.bx); S.bp0 = l * 16; S.per_b = 4; S.khalf_bytes = 2048;
;             pg8::EpiF32s E{(float*)(ws + WS_SC), 1024, RS, M, 1.f / D, EPS, 0.044194173824159216f, 32, (LAS float*)(F.lds + RING_BYTES)};
;             pg8::gemm_phase<pg8::EpiF32s, pg8::BatchBOrder<2>, true, true>(F.lds + RING_OFF, g, S, E, F.tid); AMP_END(10);
.LBB0_1022:
	s_cmp_le_i32 s62, s27
	s_cselect_b64 s[12:13], -1, 0
	s_and_b64 s[10:11], s[12:13], s[10:11]
	s_andn2_b64 vcc, exec, s[10:11]
	s_cbranch_vccnz .LBB0_1052
	v_readlane_b32 s10, v252, 1
	v_readlane_b32 s11, v252, 2
	s_mov_b32 s12, -1
	s_mov_b32 s14, s3
	v_readlane_b32 s27, v252, 0
	v_mov_b32_e32 v0, 0x23200
	ds_read_b32 v0, v0
	s_waitcnt lgkmcnt(0)
	v_readfirstlane_b32 s28, v0
	s_nop 1
	v_readlane_b32 s0, v252, 8
	s_waitcnt vmcnt(0)
	v_mbcnt_lo_u32_b32 v0, s12, 0
	v_mbcnt_hi_u32_b32 v0, s12, v0
	v_add_u32_e32 v14, s0, v0
	s_cmpk_gt_i32 s28, 0xff
	s_nop 0
	v_readfirstlane_b32 s18, v14
	s_cbranch_scc1 .LBB0_1052
	s_ashr_i32 s30, s28, 31
	s_lshr_b32 s12, s30, 29
	s_add_i32 s20, s28, s12
	s_and_b32 s12, s20, -8
	s_sub_i32 s19, s28, s12
	s_cmp_gt_i32 s19, -1
	s_mov_b64 s[12:13], -1
	s_cbranch_scc0 .LBB0_1026
	s_lshl_b32 s15, s19, 5
	s_mov_b64 s[12:13], 0

; __device__ __forceinline__ unsigned xb_add(unsigned* p, unsigned v) { return __hip_atomic_fetch_add(p, v, __ATOMIC_RELAXED, __HIP_MEMORY_SCOPE_AGENT); }
; __device__ __forceinline__ void xcd_barrier(const XcdBarrier& b) {
;     ...
;         const unsigned old = xb_add(&bar[XB_XSUB(b.x)], 1u);
;         const unsigned gen = old / nloc;
;         if (old + 1u == (gen + 1u) * nloc) {
;             __builtin_amdgcn_fence(__ATOMIC_RELEASE, "agent");
;             asm volatile("s_waitcnt vmcnt(0)" ::: "memory");
;             const unsigned og = xb_add(&bar[XB_TOP], 1u);
;             const unsigned tg = og / nx;
;             if (og + 1u == (tg + 1u) * nx) xb_add(&bar[XB_TOPGEN], 1u);
.LBB0_1083:
	s_andn2_saveexec_b64 s[14:15], s[14:15]
	s_cbranch_execz .LBB0_1101
	s_mov_b64 s[14:15], exec
	s_waitcnt lgkmcnt(0)
	s_waitcnt vmcnt(0)
	v_mbcnt_lo_u32_b32 v1, s14, 0
	v_mbcnt_hi_u32_b32 v1, s15, v1
	v_cmp_eq_u32_e32 vcc, 0, v1
	s_and_saveexec_b64 s[16:17], vcc
	s_cbranch_execz .LBB0_1086
	s_bcnt1_i32_b64 s14, s[14:15]
	v_readlane_b32 s0, v252, 57
	v_mov_b32_e32 v2, s14
	v_readlane_b32 s1, v252, 58
	s_nop 4
	global_atomic_add v2, v64, v2, s[0:1] sc0

; #define GAS __attribute__((address_space(1)))
; __device__ __forceinline__ void xsoftmax_phase(const Frame& F, const float* __restrict__ SC, bf16* __restrict__ P) {
;     const int lane = F.lane, gw = F.bx * NWAVES + F.wave, NGW = F.G * NWAVES;
;     for (int m0 = gw; m0 < M; m0 += 4 * NGW) {
;         f32x4 s[4][4];
; #pragma unroll
;         for (int i = 0; i < 4; ++i) { const int m = m0 + i * NGW; const bool ok = m < M; const size_t mm = ok ? m : m0;
; #pragma unroll
;             for (int h = 0; h < 4; ++h) { const f32x4 a = *(const GAS f32x4*)(SC + mm * 1024 + h * 256 + 4 * lane), b2 = *(const GAS f32x4*)(SC + ((size_t)M + mm) * 1024 + h * 256 + 4 * lane); s[i][h] = a + b2; } }
; #pragma unroll
;         for (int i = 0; i < 4; ++i) { const int m = m0 + i * NGW; if (m >= M) break;
.LBB0_1102:
	s_cmp_le_i32 s62, s27
	s_cselect_b64 s[12:13], -1, 0
	s_and_b64 s[10:11], s[12:13], s[10:11]
	s_andn2_b64 vcc, exec, s[10:11]
	s_cbranch_vccnz .LBB0_1110
	v_readlane_b32 s10, v252, 1
	v_readlane_b32 s11, v252, 2
	v_readlane_b32 s13, v252, 0
	s_mov_b32 s12, -1
	v_mov_b32_e32 v0, 0x23208
	ds_read_b32 v0, v0
	s_waitcnt lgkmcnt(0)
	v_readfirstlane_b32 s14, v0
	s_nop 1
	s_mov_b32 s15, s3
	v_readlane_b32 s0, v252, 8
	s_waitcnt vmcnt(0)
	v_mbcnt_lo_u32_b32 v0, s12, 0
	v_mbcnt_hi_u32_b32 v0, s12, v0
	v_add_u32_e32 v0, s0, v0
	s_nop 0
	v_readfirstlane_b32 s12, v0
	s_ashr_i32 s12, s12, 6
	s_lshl_b32 s12, s12, 2
	s_add_i32 s12, s12, s14
	s_cmpk_gt_i32 s12, 0x1fff
	s_cbranch_scc1 .LBB0_1110
	s_load_dwordx2 s[10:11], s[10:11], 0x100
	v_lshlrev_b32_e32 v0, 2, v0
	v_and_b32_e32 v8, 0xfc, v0
	s_movk_i32 s14, 0x80
	v_bitop3_b32 v9, v0, 4, v229 bitop3:0x6c
	s_waitcnt lgkmcnt(0)
	s_add_u32 s20, s10, 0x27600000
	v_bitop3_b32 v26, v0, 8, v229 bitop3:0x6c
	v_bitop3_b32 v27, v0, 16, v229 bitop3:0x6c
	v_bitop3_b32 v28, v0, 32, v229 bitop3:0x6c
	v_bitop3_b32 v29, v0, 64, v229 bitop3:0x6c
	v_bitop3_b32 v30, v0, s14, v229 bitop3:0x6c
	v_lshlrev_b32_e32 v0, 1, v8
	v_mov_b32_e32 v1, v64
	s_addc_u32 s21, s11, 0
	v_lshl_add_u64 v[0:1], s[10:11], 0, v[0:1]
	s_mov_b64 s[10:11], 0x2b600000
	s_mov_b32 s22, 1
	v_lshl_add_u64 v[10:11], v[0:1], 0, s[10:11]
	s_mov_b32 s23, 2
	s_mov_b32 s24, 3
	s_brev_b32 s0, 64
	s_mov_b64 s[26:27], 0x2000000
	s_branch .LBB0_1106
.LBB0_1105:
	s_add_i32 s10, s10, s22
	s_add_i32 s10, s10, s22
	s_add_i32 s12, s10, s22
	s_cmpk_lt_i32 s12, 0x2000
	s_branch .LBB0_1110

;     __host__ __device__ bool next(int i, Unit& u) const { if (!StaticOrder::next(i, u)) return false; u.nt = nt8 + ntb; return true; }
; #define AMP_T0() const unsigned long long at0_ = (PROBE_AMP != 0) ? __builtin_amdgcn_s_memrealtime() : 0ull
; #define AMP_END(bit) do { if (PROBE_AMP & (1u << (bit))) { __syncthreads(); const unsigned long long at1_ = __builtin_amdgcn_s_memrealtime(), tgt_ = at1_ + AMP_K * (at1_ - at0_); \
;         while (__builtin_amdgcn_s_memrealtime() < tgt_) __builtin_amdgcn_s_sleep(16); } } while (0)
;     __host__ __device__ bool next(int i, Unit& u) const {
;         if (!StaticOrder::next(i, u)) return false;
;         const int b = u.pm >> 3, slot = u.pn, pn = SPLITK == 2 ? slot >> 1 : slot, kh = SPLITK == 2 ? (slot & 1) : 0;
;         u.pn = bp0 + b * per_b + pn; u.on = pn; u.om = kh * nM + u.pm; u.aoff = kh * khalf_bytes; u.boff = kh * khalf_bytes;
;         return true;
;     }
; __global__ void __launch_bounds__(NTHREADS, 2) fwd(Args args) {
;     ...
;         if (IN(pb + PH_O)) { PHASE_BEGIN(); AMP_T0();
;             pg8::Gemm g{(const bf16*)(ws + WS_PR), (const bf16*)(ws + WS_VWO), M, D, 1024, 1024, 1024}; pg8::BatchBOrder<1> S; S.init(M, D, F.G, F.bx); S.bp0 = l * 32; S.per_b = 8; S.khalf_bytes = 0;
;             pg8::EpiResid E{XN, ka_->in[28] + (size_t)l * D, RS, M, nullptr, (float*)(ws + WS_SLOT) + (size_t)(l * 3 + 1) * 32 * 8 * 256, (unsigned*)(ws + WS_CTL) + CW_RCNT + (l * 3 + 1) * 32 * 64, 1.f / D, EPS, K8U[l] ? ws + WS_X8 : nullptr};
;             pg8::gemm_phase<pg8::EpiResid, pg8::BatchBOrder<1>, false, true>(F.lds + RING_OFF, g, S, E, F.tid); AMP_END(11);
.LBB0_1160:
	s_cmp_le_i32 s62, s27
	s_cselect_b64 s[12:13], -1, 0
	s_and_b64 s[10:11], s[12:13], s[10:11]
	s_andn2_b64 vcc, exec, s[10:11]
	s_cbranch_vccnz .LBB0_1269
	v_readlane_b32 s18, v252, 1
	v_readlane_b32 s19, v252, 2
	v_mov_b32_e32 v0, 0x23200
	ds_read_b32 v0, v0
	s_waitcnt lgkmcnt(0)
	v_readfirstlane_b32 s15, v0
	s_nop 1
	s_mov_b32 s10, -1
	s_mov_b32 s14, s3
	v_readlane_b32 s28, v252, 0
	v_readlane_b32 s0, v252, 8
	s_waitcnt vmcnt(0)
	v_mbcnt_lo_u32_b32 v0, s10, 0
	v_mbcnt_hi_u32_b32 v0, s10, v0
	v_add_u32_e32 v170, s0, v0
	s_cmpk_gt_i32 s15, 0xff
	s_nop 0
	v_readfirstlane_b32 s27, v170
	s_cbranch_scc1 .LBB0_1269
	s_ashr_i32 s30, s15, 31
	s_lshr_b32 s10, s30, 29
	s_add_i32 s20, s15, s10
	s_and_b32 s10, s20, -8
	s_sub_i32 s17, s15, s10
	s_cmp_gt_i32 s17, -1
	s_mov_b64 s[12:13], -1
	s_cbranch_scc0 .LBB0_1164
	s_lshl_b32 s16, s17, 5
	s_mov_b64 s[12:13], 0

; #define LAS __attribute__((address_space(3)))
; #define LAS __attribute__((address_space(3)))
; #define AMP_T0() const unsigned long long at0_ = (PROBE_AMP != 0) ? __builtin_amdgcn_s_memrealtime() : 0ull
; __global__ void __launch_bounds__(NTHREADS, 2) fwd(Args args) {
;     ...
;         if (IN(pb + PH_UP)) { PHASE_BEGIN(); AMP_T0();
;             const int k8u = K8U[l]; const bf16* A0 = k8u ? (const bf16*)(ws + WS_X8) : XN;
;             pg8::Gemm g{A0, (const bf16*)(wl + WL_UP), M, DFF, D, 0, 0}; pg8::MixedOrder S; S.init(M, DFF, F.G, F.bx); S.nt8 = k8u / 128; S.ntb = (D - k8u) / 64;
;             S.jumpA = k8u ? (long long)((const char*)XN - (const char*)A0) + k8u : 0; S.jumpB = k8u; S.sclA = 0x7b7b7b7b; S.sclB = 0x78787878;
;             pg8::EpiBf16<1> E{(bf16*)(ws + WS_H), DFF, nullptr, 0, RS, M, 1.f / D, EPS, (LAS float*)(F.lds + RING_BYTES), K8L[l] / 256, (LAS int*)(F.lds + MISC_OFF) + 16, (l * 4 + 2) * 64};
.LBB0_1319:
	s_cmp_le_i32 s62, s27
	s_cselect_b64 s[12:13], -1, 0
	s_and_b64 s[10:11], s[12:13], s[10:11]
	s_andn2_b64 vcc, exec, s[10:11]
	s_cbranch_vccnz .LBB0_1362
	v_readlane_b32 s10, v252, 1
	v_readlane_b32 s11, v252, 2
	v_mov_b32_e32 v0, 0x23200
	ds_read_b32 v0, v0
	s_waitcnt lgkmcnt(0)
	v_readfirstlane_b32 s28, v0
	s_nop 1
	s_mov_b32 s12, -1
	s_mov_b32 s18, s3
	v_readlane_b32 s30, v252, 0
	s_ashr_i32 s19, s18, 31
	s_waitcnt vmcnt(0)
	v_mbcnt_lo_u32_b32 v0, s12, 0
	s_lshl_b64 s[14:15], s[18:19], 2
	v_mbcnt_hi_u32_b32 v0, s12, v0
	s_getpc_b64 s[12:13]
	s_add_u32 s12, s12, _ZL3K8U@rel32@lo+4
	s_addc_u32 s13, s13, _ZL3K8U@rel32@hi+12
	s_add_u32 s12, s12, s14
	s_addc_u32 s13, s13, s15
	s_getpc_b64 s[16:17]
	s_add_u32 s16, s16, _ZL3K8L@rel32@lo+4
	s_addc_u32 s17, s17, _ZL3K8L@rel32@hi+12
	v_readlane_b32 s0, v252, 8
	s_add_u32 s14, s16, s14
	s_addc_u32 s15, s17, s15
	v_add_u32_e32 v8, s0, v0
	s_cmpk_lt_i32 s28, 0x400
	s_cselect_b64 s[16:17], -1, 0
	s_cmpk_gt_i32 s28, 0x3ff
	v_readfirstlane_b32 s22, v8
	s_cbranch_scc1 .LBB0_1326
	s_ashr_i32 s20, s28, 31
	s_lshr_b32 s20, s20, 29
	s_add_i32 s23, s28, s20
	s_and_b32 s20, s23, -8
	s_sub_i32 s24, s28, s20
	s_cmp_gt_i32 s24, -1
	s_mov_b64 s[20:21], -1
	s_cbranch_scc0 .LBB0_1323
	s_lshl_b32 s25, s24, 7
	s_mov_b64 s[20:21], 0

; #define AMP_T0() const unsigned long long at0_ = (PROBE_AMP != 0) ? __builtin_amdgcn_s_memrealtime() : 0ull
; #define AMP_END(bit) do { if (PROBE_AMP & (1u << (bit))) { __syncthreads(); const unsigned long long at1_ = __builtin_amdgcn_s_memrealtime(), tgt_ = at1_ + AMP_K * (at1_ - at0_); \
;         while (__builtin_amdgcn_s_memrealtime() < tgt_) __builtin_amdgcn_s_sleep(16); } } while (0)
; __global__ void __launch_bounds__(NTHREADS, 2) fwd(Args args) {
;     ...
;         if (IN(pb + PH_DOWN)) { PHASE_BEGIN(); AMP_T0();
;             pg8::Gemm g{(const bf16*)(ws + WS_H), (const bf16*)(wl + WL_DOWN), M, D, DFF, 0, 0}; pg8::MixedOrder S; S.init(M, D, F.G, F.bx); const int k8 = K8L[l]; S.nt8 = k8 / 128; S.ntb = (DFF - k8) / 64; S.jumpA = k8; S.jumpB = k8; S.sclA = 0x7b7b7b7b; S.sclB = 0x77777777;
;             pg8::EpiResid E{XN, ka_->in[30] + (size_t)l * D, RS, M, (l + 1 < DEPTH) ? nullptr : X, (float*)(ws + WS_SLOT) + (size_t)(l * 3 + 2) * 32 * 8 * 256, (unsigned*)(ws + WS_CTL) + CW_RCNT + (l * 3 + 2) * 32 * 64, 1.f / D, EPS};
;             pg8::gemm_phase<pg8::EpiResid, pg8::MixedOrder, false, true>(F.lds + RING_OFF, g, S, E, F.tid); AMP_END(13);
.LBB0_1412:
	s_cmp_le_i32 s62, s27
	s_cselect_b64 s[12:13], -1, 0
	s_and_b64 s[10:11], s[12:13], s[10:11]
	s_andn2_b64 vcc, exec, s[10:11]
	s_cbranch_vccnz .LBB0_1522
	v_readlane_b32 s10, v252, 1
	v_readlane_b32 s11, v252, 2
	v_mov_b32_e32 v0, 0x23200
	ds_read_b32 v0, v0
	s_waitcnt lgkmcnt(0)
	v_readfirstlane_b32 s28, v0
	s_nop 1
	s_mov_b32 s12, -1
	s_mov_b32 s14, s3
	v_readlane_b32 s30, v252, 0
	v_readlane_b32 s0, v252, 8
	s_waitcnt vmcnt(0)
	v_mbcnt_lo_u32_b32 v0, s12, 0
	v_mbcnt_hi_u32_b32 v0, s12, v0
	v_add_u32_e32 v181, s0, v0
	s_cmpk_gt_i32 s28, 0xff
	s_nop 0
	v_readfirstlane_b32 s27, v181
	s_cbranch_scc1 .LBB0_1522
	s_ashr_i32 s15, s14, 31
	s_lshl_b64 s[12:13], s[14:15], 2
	s_getpc_b64 s[16:17]
	s_add_u32 s16, s16, _ZL3K8L@rel32@lo+4
	s_addc_u32 s17, s17, _ZL3K8L@rel32@hi+12
	s_add_u32 s12, s16, s12
	s_addc_u32 s13, s17, s13
	s_ashr_i32 s31, s28, 31
	s_lshr_b32 s16, s31, 29
	s_add_i32 s20, s28, s16
	s_and_b32 s16, s20, -8
	s_sub_i32 s19, s28, s16
	s_cmp_gt_i32 s19, -1
	s_mov_b64 s[16:17], -1
	s_cbranch_scc0 .LBB0_1416
	s_lshl_b32 s18, s19, 5
	s_mov_b64 s[16:17], 0

; __device__ __forceinline__ unsigned xb_add(unsigned* p, unsigned v) { return __hip_atomic_fetch_add(p, v, __ATOMIC_RELAXED, __HIP_MEMORY_SCOPE_AGENT); }
; __device__ __forceinline__ void xcd_barrier(const XcdBarrier& b) {
;     ...
;         const unsigned old = xb_add(&bar[XB_XSUB(b.x)], 1u);
;         const unsigned gen = old / nloc;
;         if (old + 1u == (gen + 1u) * nloc) {
;             __builtin_amdgcn_fence(__ATOMIC_RELEASE, "agent");
;             asm volatile("s_waitcnt vmcnt(0)" ::: "memory");
;             const unsigned og = xb_add(&bar[XB_TOP], 1u);
;             const unsigned tg = og / nx;
;             if (og + 1u == (tg + 1u) * nx) xb_add(&bar[XB_TOPGEN], 1u);
.LBB0_1554:
	s_mov_b64 s[12:13], exec
	s_waitcnt lgkmcnt(0)
	s_waitcnt vmcnt(0)
	v_mbcnt_lo_u32_b32 v1, s12, 0
	v_mbcnt_hi_u32_b32 v1, s13, v1
	v_cmp_eq_u32_e32 vcc, 0, v1
	s_and_saveexec_b64 s[14:15], vcc
	s_cbranch_execz .LBB0_1556
	s_bcnt1_i32_b64 s12, s[12:13]
	v_readlane_b32 s0, v252, 57
	v_mov_b32_e32 v2, s12
	v_readlane_b32 s1, v252, 58
	s_nop 4
	global_atomic_add v2, v64, v2, s[0:1] sc0
